# memory K/V projection (kv2): coalesced loads staged through per-wave LDS with XOR swizzle (same MFMA order), phase 24->17us
# speedup vs baseline: 1.1156x; 1.0075x over previous
.LBB0_533:
	v_mbcnt_lo_u32_b32 v236, -1, 0
	v_mbcnt_hi_u32_b32 v236, -1, v236
	v_lshrrev_b32_e32 v237, 4, v236
	v_and_b32_e32 v238, 15, v236
	v_lshlrev_b32_e32 v239, 11, v237
	v_lshl_add_u32 v239, v238, 4, v239
	v_lshlrev_b32_e32 v240, 11, v28
	v_lshl_add_u32 v240, v29, 2, v240
	v_sub_u32_e32 v239, v239, v240
	v_ashrrev_i32_e32 v240, 31, v239
	v_mov_b32_e32 v242, v239
	v_mov_b32_e32 v243, v240
	v_lshl_add_u64 v[192:193], v[24:25], 0, v[242:243]
	v_lshl_add_u64 v[208:209], v[26:27], 0, v[242:243]
	s_mov_b64 s[10:11], 0x2000
	v_lshl_add_u64 v[194:195], v[192:193], 0, s[10:11]
	v_lshl_add_u64 v[210:211], v[208:209], 0, s[10:11]
	v_lshl_add_u64 v[196:197], v[194:195], 0, s[10:11]
	v_lshl_add_u64 v[212:213], v[210:211], 0, s[10:11]
	v_lshl_add_u64 v[198:199], v[196:197], 0, s[10:11]
	v_lshl_add_u64 v[214:215], v[212:213], 0, s[10:11]
	v_lshl_add_u64 v[200:201], v[198:199], 0, s[10:11]
	v_lshl_add_u64 v[216:217], v[214:215], 0, s[10:11]
	v_lshl_add_u64 v[202:203], v[200:201], 0, s[10:11]
	v_lshl_add_u64 v[218:219], v[216:217], 0, s[10:11]
	v_lshl_add_u64 v[204:205], v[202:203], 0, s[10:11]
	v_lshl_add_u64 v[220:221], v[218:219], 0, s[10:11]
	v_lshl_add_u64 v[206:207], v[204:205], 0, s[10:11]
	v_lshl_add_u64 v[222:223], v[220:221], 0, s[10:11]
	v_readlane_b32 s10, v254, 25
	s_nop 3
	s_sub_i32 s10, s10, 4
	s_lshl_b32 s10, s10, 15
	v_mov_b32_e32 v240, v237
	v_xor_b32_e32 v240, v238, v240
	v_lshlrev_b32_e32 v240, 4, v240
	v_lshl_add_u32 v240, v237, 8, v240
	v_add_u32_e32 v224, s10, v240
	v_add_u32_e32 v240, 4, v237
	v_xor_b32_e32 v240, v238, v240
	v_lshlrev_b32_e32 v240, 4, v240
	v_lshl_add_u32 v240, v237, 8, v240
	v_add_u32_e32 v225, s10, v240
	v_add_u32_e32 v240, 8, v237
	v_xor_b32_e32 v240, v238, v240
	v_lshlrev_b32_e32 v240, 4, v240
	v_lshl_add_u32 v240, v237, 8, v240
	v_add_u32_e32 v226, s10, v240
	v_add_u32_e32 v240, 12, v237
	v_xor_b32_e32 v240, v238, v240
	v_lshlrev_b32_e32 v240, 4, v240
	v_lshl_add_u32 v240, v237, 8, v240
	v_add_u32_e32 v227, s10, v240
	v_lshrrev_b32_e32 v240, 2, v29
	v_and_b32_e32 v241, 15, v28
	v_xor_b32_e32 v240, v240, v241
	v_lshlrev_b32_e32 v240, 4, v240
	v_lshl_add_u32 v240, v28, 8, v240
	v_add_u32_e32 v228, s10, v240
	v_xor_b32_e32 v229, 32, v228
	v_xor_b32_e32 v230, 64, v228
	v_xor_b32_e32 v231, 0x60, v228
	v_xor_b32_e32 v232, 0x80, v228
	v_xor_b32_e32 v233, 0xa0, v228
	v_xor_b32_e32 v234, 0xc0, v228
	v_xor_b32_e32 v235, 0xe0, v228
	global_load_dwordx4 v[32:35], v[192:193], off
	global_load_dwordx4 v[36:39], v[208:209], off
	global_load_dwordx4 v[40:43], v[194:195], off
	global_load_dwordx4 v[44:47], v[210:211], off
	global_load_dwordx4 v[48:51], v[196:197], off
	global_load_dwordx4 v[52:55], v[212:213], off
	global_load_dwordx4 v[56:59], v[198:199], off
	global_load_dwordx4 v[60:63], v[214:215], off
	global_load_dwordx4 v[64:67], v[200:201], off
	global_load_dwordx4 v[68:71], v[216:217], off
	global_load_dwordx4 v[72:75], v[202:203], off
	global_load_dwordx4 v[76:79], v[218:219], off
	global_load_dwordx4 v[80:83], v[204:205], off
	global_load_dwordx4 v[84:87], v[220:221], off
	global_load_dwordx4 v[88:91], v[206:207], off
	global_load_dwordx4 v[92:95], v[222:223], off
	global_load_dwordx4 v[96:99], v[192:193], off offset:256
	global_load_dwordx4 v[100:103], v[208:209], off offset:256
	global_load_dwordx4 v[104:107], v[194:195], off offset:256
	global_load_dwordx4 v[108:111], v[210:211], off offset:256
	global_load_dwordx4 v[112:115], v[196:197], off offset:256
	global_load_dwordx4 v[116:119], v[212:213], off offset:256
	global_load_dwordx4 v[120:123], v[198:199], off offset:256
	global_load_dwordx4 v[124:127], v[214:215], off offset:256
	global_load_dwordx4 v[128:131], v[200:201], off offset:256
	global_load_dwordx4 v[132:135], v[216:217], off offset:256
	global_load_dwordx4 v[136:139], v[202:203], off offset:256
	global_load_dwordx4 v[140:143], v[218:219], off offset:256
	global_load_dwordx4 v[144:147], v[204:205], off offset:256
	global_load_dwordx4 v[148:151], v[220:221], off offset:256
	global_load_dwordx4 v[152:155], v[206:207], off offset:256
	global_load_dwordx4 v[156:159], v[222:223], off offset:256
	s_waitcnt vmcnt(16)
	ds_write_b128 v224, v[32:35] offset:0
	ds_write_b128 v224, v[36:39] offset:8192
	ds_write_b128 v225, v[40:43] offset:1024
	ds_write_b128 v225, v[44:47] offset:9216
	ds_write_b128 v226, v[48:51] offset:2048
	ds_write_b128 v226, v[52:55] offset:10240
	ds_write_b128 v227, v[56:59] offset:3072
	ds_write_b128 v227, v[60:63] offset:11264
	ds_write_b128 v224, v[64:67] offset:4096
	ds_write_b128 v224, v[68:71] offset:12288
	ds_write_b128 v225, v[72:75] offset:5120
	ds_write_b128 v225, v[76:79] offset:13312
	ds_write_b128 v226, v[80:83] offset:6144
	ds_write_b128 v226, v[84:87] offset:14336
	ds_write_b128 v227, v[88:91] offset:7168
	ds_write_b128 v227, v[92:95] offset:15360
	s_waitcnt lgkmcnt(0)
	global_load_dwordx4 v[32:35], v[192:193], off offset:512
	global_load_dwordx4 v[36:39], v[208:209], off offset:512
	global_load_dwordx4 v[40:43], v[194:195], off offset:512
	global_load_dwordx4 v[44:47], v[210:211], off offset:512
	global_load_dwordx4 v[48:51], v[196:197], off offset:512
	global_load_dwordx4 v[52:55], v[212:213], off offset:512
	global_load_dwordx4 v[56:59], v[198:199], off offset:512
	global_load_dwordx4 v[60:63], v[214:215], off offset:512
	global_load_dwordx4 v[64:67], v[200:201], off offset:512
	global_load_dwordx4 v[68:71], v[216:217], off offset:512
	global_load_dwordx4 v[72:75], v[202:203], off offset:512
	global_load_dwordx4 v[76:79], v[218:219], off offset:512
	global_load_dwordx4 v[80:83], v[204:205], off offset:512
	global_load_dwordx4 v[84:87], v[220:221], off offset:512
	global_load_dwordx4 v[88:91], v[206:207], off offset:512
	global_load_dwordx4 v[92:95], v[222:223], off offset:512
	ds_read_b128 v[160:163], v228 offset:0
	ds_read_b128 v[164:167], v228 offset:8192
	ds_read_b128 v[168:171], v229 offset:0
	ds_read_b128 v[172:175], v229 offset:8192
	ds_read_b128 v[176:179], v230 offset:0
	ds_read_b128 v[180:183], v230 offset:8192
	ds_read_b128 v[184:187], v231 offset:0
	ds_read_b128 v[188:191], v231 offset:8192
	s_waitcnt lgkmcnt(6)
	v_mfma_f32_32x32x16_bf16 v[0:15], v[160:163], v[164:167], v[0:15]
	s_waitcnt lgkmcnt(4)
	v_mfma_f32_32x32x16_bf16 v[0:15], v[168:171], v[172:175], v[0:15]
	s_waitcnt lgkmcnt(2)
	v_mfma_f32_32x32x16_bf16 v[0:15], v[176:179], v[180:183], v[0:15]
	s_waitcnt lgkmcnt(0)
	v_mfma_f32_32x32x16_bf16 v[0:15], v[184:187], v[188:191], v[0:15]
	ds_read_b128 v[160:163], v232 offset:0
	ds_read_b128 v[164:167], v232 offset:8192
	ds_read_b128 v[168:171], v233 offset:0
	ds_read_b128 v[172:175], v233 offset:8192
	ds_read_b128 v[176:179], v234 offset:0
	ds_read_b128 v[180:183], v234 offset:8192
	ds_read_b128 v[184:187], v235 offset:0
	ds_read_b128 v[188:191], v235 offset:8192
	s_waitcnt lgkmcnt(6)
	v_mfma_f32_32x32x16_bf16 v[0:15], v[160:163], v[164:167], v[0:15]
	s_waitcnt lgkmcnt(4)
	v_mfma_f32_32x32x16_bf16 v[0:15], v[168:171], v[172:175], v[0:15]
	s_waitcnt lgkmcnt(2)
	v_mfma_f32_32x32x16_bf16 v[0:15], v[176:179], v[180:183], v[0:15]
	s_waitcnt lgkmcnt(0)
	v_mfma_f32_32x32x16_bf16 v[0:15], v[184:187], v[188:191], v[0:15]
	s_waitcnt vmcnt(16)
	ds_write_b128 v224, v[96:99] offset:16384
	ds_write_b128 v224, v[100:103] offset:24576
	ds_write_b128 v225, v[104:107] offset:17408
	ds_write_b128 v225, v[108:111] offset:25600
	ds_write_b128 v226, v[112:115] offset:18432
	ds_write_b128 v226, v[116:119] offset:26624
	ds_write_b128 v227, v[120:123] offset:19456
	ds_write_b128 v227, v[124:127] offset:27648
	ds_write_b128 v224, v[128:131] offset:20480
	ds_write_b128 v224, v[132:135] offset:28672
	ds_write_b128 v225, v[136:139] offset:21504
	ds_write_b128 v225, v[140:143] offset:29696
	ds_write_b128 v226, v[144:147] offset:22528
	ds_write_b128 v226, v[148:151] offset:30720
	ds_write_b128 v227, v[152:155] offset:23552
	ds_write_b128 v227, v[156:159] offset:31744
	s_waitcnt lgkmcnt(0)
	global_load_dwordx4 v[96:99], v[192:193], off offset:768
	global_load_dwordx4 v[100:103], v[208:209], off offset:768
	global_load_dwordx4 v[104:107], v[194:195], off offset:768
	global_load_dwordx4 v[108:111], v[210:211], off offset:768
	global_load_dwordx4 v[112:115], v[196:197], off offset:768
	global_load_dwordx4 v[116:119], v[212:213], off offset:768
	global_load_dwordx4 v[120:123], v[198:199], off offset:768
	global_load_dwordx4 v[124:127], v[214:215], off offset:768
	global_load_dwordx4 v[128:131], v[200:201], off offset:768
	global_load_dwordx4 v[132:135], v[216:217], off offset:768
	global_load_dwordx4 v[136:139], v[202:203], off offset:768
	global_load_dwordx4 v[140:143], v[218:219], off offset:768
	global_load_dwordx4 v[144:147], v[204:205], off offset:768
	global_load_dwordx4 v[148:151], v[220:221], off offset:768
	global_load_dwordx4 v[152:155], v[206:207], off offset:768
	global_load_dwordx4 v[156:159], v[222:223], off offset:768
	ds_read_b128 v[160:163], v228 offset:16384
	ds_read_b128 v[164:167], v228 offset:24576
	ds_read_b128 v[168:171], v229 offset:16384
	ds_read_b128 v[172:175], v229 offset:24576
	ds_read_b128 v[176:179], v230 offset:16384
	ds_read_b128 v[180:183], v230 offset:24576
	ds_read_b128 v[184:187], v231 offset:16384
	ds_read_b128 v[188:191], v231 offset:24576
	s_waitcnt lgkmcnt(6)
	v_mfma_f32_32x32x16_bf16 v[0:15], v[160:163], v[164:167], v[0:15]
	s_waitcnt lgkmcnt(4)
	v_mfma_f32_32x32x16_bf16 v[0:15], v[168:171], v[172:175], v[0:15]
	s_waitcnt lgkmcnt(2)
	v_mfma_f32_32x32x16_bf16 v[0:15], v[176:179], v[180:183], v[0:15]
	s_waitcnt lgkmcnt(0)
	v_mfma_f32_32x32x16_bf16 v[0:15], v[184:187], v[188:191], v[0:15]
	ds_read_b128 v[160:163], v232 offset:16384
	ds_read_b128 v[164:167], v232 offset:24576
	ds_read_b128 v[168:171], v233 offset:16384
	ds_read_b128 v[172:175], v233 offset:24576
	ds_read_b128 v[176:179], v234 offset:16384
	ds_read_b128 v[180:183], v234 offset:24576
	ds_read_b128 v[184:187], v235 offset:16384
	ds_read_b128 v[188:191], v235 offset:24576
	s_waitcnt lgkmcnt(6)
	v_mfma_f32_32x32x16_bf16 v[0:15], v[160:163], v[164:167], v[0:15]
	s_waitcnt lgkmcnt(4)
	v_mfma_f32_32x32x16_bf16 v[0:15], v[168:171], v[172:175], v[0:15]
	s_waitcnt lgkmcnt(2)
	v_mfma_f32_32x32x16_bf16 v[0:15], v[176:179], v[180:183], v[0:15]
	s_waitcnt lgkmcnt(0)
	v_mfma_f32_32x32x16_bf16 v[0:15], v[184:187], v[188:191], v[0:15]
	s_waitcnt vmcnt(16)
	ds_write_b128 v224, v[32:35] offset:0
	ds_write_b128 v224, v[36:39] offset:8192
	ds_write_b128 v225, v[40:43] offset:1024
	ds_write_b128 v225, v[44:47] offset:9216
	ds_write_b128 v226, v[48:51] offset:2048
	ds_write_b128 v226, v[52:55] offset:10240
	ds_write_b128 v227, v[56:59] offset:3072
	ds_write_b128 v227, v[60:63] offset:11264
	ds_write_b128 v224, v[64:67] offset:4096
	ds_write_b128 v224, v[68:71] offset:12288
	ds_write_b128 v225, v[72:75] offset:5120
	ds_write_b128 v225, v[76:79] offset:13312
	ds_write_b128 v226, v[80:83] offset:6144
	ds_write_b128 v226, v[84:87] offset:14336
	ds_write_b128 v227, v[88:91] offset:7168
	ds_write_b128 v227, v[92:95] offset:15360
	s_waitcnt lgkmcnt(0)
	global_load_dwordx4 v[32:35], v[192:193], off offset:1024
	global_load_dwordx4 v[36:39], v[208:209], off offset:1024
	global_load_dwordx4 v[40:43], v[194:195], off offset:1024
	global_load_dwordx4 v[44:47], v[210:211], off offset:1024
	global_load_dwordx4 v[48:51], v[196:197], off offset:1024
	global_load_dwordx4 v[52:55], v[212:213], off offset:1024
	global_load_dwordx4 v[56:59], v[198:199], off offset:1024
	global_load_dwordx4 v[60:63], v[214:215], off offset:1024
	global_load_dwordx4 v[64:67], v[200:201], off offset:1024
	global_load_dwordx4 v[68:71], v[216:217], off offset:1024
	global_load_dwordx4 v[72:75], v[202:203], off offset:1024
	global_load_dwordx4 v[76:79], v[218:219], off offset:1024
	global_load_dwordx4 v[80:83], v[204:205], off offset:1024
	global_load_dwordx4 v[84:87], v[220:221], off offset:1024
	global_load_dwordx4 v[88:91], v[206:207], off offset:1024
	global_load_dwordx4 v[92:95], v[222:223], off offset:1024
	ds_read_b128 v[160:163], v228 offset:0
	ds_read_b128 v[164:167], v228 offset:8192
	ds_read_b128 v[168:171], v229 offset:0
	ds_read_b128 v[172:175], v229 offset:8192
	ds_read_b128 v[176:179], v230 offset:0
	ds_read_b128 v[180:183], v230 offset:8192
	ds_read_b128 v[184:187], v231 offset:0
	ds_read_b128 v[188:191], v231 offset:8192
	s_waitcnt lgkmcnt(6)
	v_mfma_f32_32x32x16_bf16 v[0:15], v[160:163], v[164:167], v[0:15]
	s_waitcnt lgkmcnt(4)
	v_mfma_f32_32x32x16_bf16 v[0:15], v[168:171], v[172:175], v[0:15]
	s_waitcnt lgkmcnt(2)
	v_mfma_f32_32x32x16_bf16 v[0:15], v[176:179], v[180:183], v[0:15]
	s_waitcnt lgkmcnt(0)
	v_mfma_f32_32x32x16_bf16 v[0:15], v[184:187], v[188:191], v[0:15]
	ds_read_b128 v[160:163], v232 offset:0
	ds_read_b128 v[164:167], v232 offset:8192
	ds_read_b128 v[168:171], v233 offset:0
	ds_read_b128 v[172:175], v233 offset:8192
	ds_read_b128 v[176:179], v234 offset:0
	ds_read_b128 v[180:183], v234 offset:8192
	ds_read_b128 v[184:187], v235 offset:0
	ds_read_b128 v[188:191], v235 offset:8192
	s_waitcnt lgkmcnt(6)
	v_mfma_f32_32x32x16_bf16 v[0:15], v[160:163], v[164:167], v[0:15]
	s_waitcnt lgkmcnt(4)
	v_mfma_f32_32x32x16_bf16 v[0:15], v[168:171], v[172:175], v[0:15]
	s_waitcnt lgkmcnt(2)
	v_mfma_f32_32x32x16_bf16 v[0:15], v[176:179], v[180:183], v[0:15]
	s_waitcnt lgkmcnt(0)
	v_mfma_f32_32x32x16_bf16 v[0:15], v[184:187], v[188:191], v[0:15]
	s_waitcnt vmcnt(16)
	ds_write_b128 v224, v[96:99] offset:16384
	ds_write_b128 v224, v[100:103] offset:24576
	ds_write_b128 v225, v[104:107] offset:17408
	ds_write_b128 v225, v[108:111] offset:25600
	ds_write_b128 v226, v[112:115] offset:18432
	ds_write_b128 v226, v[116:119] offset:26624
	ds_write_b128 v227, v[120:123] offset:19456
	ds_write_b128 v227, v[124:127] offset:27648
	ds_write_b128 v224, v[128:131] offset:20480
	ds_write_b128 v224, v[132:135] offset:28672
	ds_write_b128 v225, v[136:139] offset:21504
	ds_write_b128 v225, v[140:143] offset:29696
	ds_write_b128 v226, v[144:147] offset:22528
	ds_write_b128 v226, v[148:151] offset:30720
	ds_write_b128 v227, v[152:155] offset:23552
	ds_write_b128 v227, v[156:159] offset:31744
	s_waitcnt lgkmcnt(0)
	global_load_dwordx4 v[96:99], v[192:193], off offset:1280
	global_load_dwordx4 v[100:103], v[208:209], off offset:1280
	global_load_dwordx4 v[104:107], v[194:195], off offset:1280
	global_load_dwordx4 v[108:111], v[210:211], off offset:1280
	global_load_dwordx4 v[112:115], v[196:197], off offset:1280
	global_load_dwordx4 v[116:119], v[212:213], off offset:1280
	global_load_dwordx4 v[120:123], v[198:199], off offset:1280
	global_load_dwordx4 v[124:127], v[214:215], off offset:1280
	global_load_dwordx4 v[128:131], v[200:201], off offset:1280
	global_load_dwordx4 v[132:135], v[216:217], off offset:1280
	global_load_dwordx4 v[136:139], v[202:203], off offset:1280
	global_load_dwordx4 v[140:143], v[218:219], off offset:1280
	global_load_dwordx4 v[144:147], v[204:205], off offset:1280
	global_load_dwordx4 v[148:151], v[220:221], off offset:1280
	global_load_dwordx4 v[152:155], v[206:207], off offset:1280
	global_load_dwordx4 v[156:159], v[222:223], off offset:1280
	ds_read_b128 v[160:163], v228 offset:16384
	ds_read_b128 v[164:167], v228 offset:24576
	ds_read_b128 v[168:171], v229 offset:16384
	ds_read_b128 v[172:175], v229 offset:24576
	ds_read_b128 v[176:179], v230 offset:16384
	ds_read_b128 v[180:183], v230 offset:24576
	ds_read_b128 v[184:187], v231 offset:16384
	ds_read_b128 v[188:191], v231 offset:24576
	s_waitcnt lgkmcnt(6)
	v_mfma_f32_32x32x16_bf16 v[0:15], v[160:163], v[164:167], v[0:15]
	s_waitcnt lgkmcnt(4)
	v_mfma_f32_32x32x16_bf16 v[0:15], v[168:171], v[172:175], v[0:15]
	s_waitcnt lgkmcnt(2)
	v_mfma_f32_32x32x16_bf16 v[0:15], v[176:179], v[180:183], v[0:15]
	s_waitcnt lgkmcnt(0)
	v_mfma_f32_32x32x16_bf16 v[0:15], v[184:187], v[188:191], v[0:15]
	ds_read_b128 v[160:163], v232 offset:16384
	ds_read_b128 v[164:167], v232 offset:24576
	ds_read_b128 v[168:171], v233 offset:16384
	ds_read_b128 v[172:175], v233 offset:24576
	ds_read_b128 v[176:179], v234 offset:16384
	ds_read_b128 v[180:183], v234 offset:24576
	ds_read_b128 v[184:187], v235 offset:16384
	ds_read_b128 v[188:191], v235 offset:24576
	s_waitcnt lgkmcnt(6)
	v_mfma_f32_32x32x16_bf16 v[0:15], v[160:163], v[164:167], v[0:15]
	s_waitcnt lgkmcnt(4)
	v_mfma_f32_32x32x16_bf16 v[0:15], v[168:171], v[172:175], v[0:15]
	s_waitcnt lgkmcnt(2)
	v_mfma_f32_32x32x16_bf16 v[0:15], v[176:179], v[180:183], v[0:15]
	s_waitcnt lgkmcnt(0)
	v_mfma_f32_32x32x16_bf16 v[0:15], v[184:187], v[188:191], v[0:15]
	s_waitcnt vmcnt(16)
	ds_write_b128 v224, v[32:35] offset:0
	ds_write_b128 v224, v[36:39] offset:8192
	ds_write_b128 v225, v[40:43] offset:1024
	ds_write_b128 v225, v[44:47] offset:9216
	ds_write_b128 v226, v[48:51] offset:2048
	ds_write_b128 v226, v[52:55] offset:10240
	ds_write_b128 v227, v[56:59] offset:3072
	ds_write_b128 v227, v[60:63] offset:11264
	ds_write_b128 v224, v[64:67] offset:4096
	ds_write_b128 v224, v[68:71] offset:12288
	ds_write_b128 v225, v[72:75] offset:5120
	ds_write_b128 v225, v[76:79] offset:13312
	ds_write_b128 v226, v[80:83] offset:6144
	ds_write_b128 v226, v[84:87] offset:14336
	ds_write_b128 v227, v[88:91] offset:7168
	ds_write_b128 v227, v[92:95] offset:15360
	s_waitcnt lgkmcnt(0)
	global_load_dwordx4 v[32:35], v[192:193], off offset:1536
	global_load_dwordx4 v[36:39], v[208:209], off offset:1536
	global_load_dwordx4 v[40:43], v[194:195], off offset:1536
	global_load_dwordx4 v[44:47], v[210:211], off offset:1536
	global_load_dwordx4 v[48:51], v[196:197], off offset:1536
	global_load_dwordx4 v[52:55], v[212:213], off offset:1536
	global_load_dwordx4 v[56:59], v[198:199], off offset:1536
	global_load_dwordx4 v[60:63], v[214:215], off offset:1536
	global_load_dwordx4 v[64:67], v[200:201], off offset:1536
	global_load_dwordx4 v[68:71], v[216:217], off offset:1536
	global_load_dwordx4 v[72:75], v[202:203], off offset:1536
	global_load_dwordx4 v[76:79], v[218:219], off offset:1536
	global_load_dwordx4 v[80:83], v[204:205], off offset:1536
	global_load_dwordx4 v[84:87], v[220:221], off offset:1536
	global_load_dwordx4 v[88:91], v[206:207], off offset:1536
	global_load_dwordx4 v[92:95], v[222:223], off offset:1536
	ds_read_b128 v[160:163], v228 offset:0
	ds_read_b128 v[164:167], v228 offset:8192
	ds_read_b128 v[168:171], v229 offset:0
	ds_read_b128 v[172:175], v229 offset:8192
	ds_read_b128 v[176:179], v230 offset:0
	ds_read_b128 v[180:183], v230 offset:8192
	ds_read_b128 v[184:187], v231 offset:0
	ds_read_b128 v[188:191], v231 offset:8192
	s_waitcnt lgkmcnt(6)
	v_mfma_f32_32x32x16_bf16 v[0:15], v[160:163], v[164:167], v[0:15]
	s_waitcnt lgkmcnt(4)
	v_mfma_f32_32x32x16_bf16 v[0:15], v[168:171], v[172:175], v[0:15]
	s_waitcnt lgkmcnt(2)
	v_mfma_f32_32x32x16_bf16 v[0:15], v[176:179], v[180:183], v[0:15]
	s_waitcnt lgkmcnt(0)
	v_mfma_f32_32x32x16_bf16 v[0:15], v[184:187], v[188:191], v[0:15]
	ds_read_b128 v[160:163], v232 offset:0
	ds_read_b128 v[164:167], v232 offset:8192
	ds_read_b128 v[168:171], v233 offset:0
	ds_read_b128 v[172:175], v233 offset:8192
	ds_read_b128 v[176:179], v234 offset:0
	ds_read_b128 v[180:183], v234 offset:8192
	ds_read_b128 v[184:187], v235 offset:0
	ds_read_b128 v[188:191], v235 offset:8192
	s_waitcnt lgkmcnt(6)
	v_mfma_f32_32x32x16_bf16 v[0:15], v[160:163], v[164:167], v[0:15]
	s_waitcnt lgkmcnt(4)
	v_mfma_f32_32x32x16_bf16 v[0:15], v[168:171], v[172:175], v[0:15]
	s_waitcnt lgkmcnt(2)
	v_mfma_f32_32x32x16_bf16 v[0:15], v[176:179], v[180:183], v[0:15]
	s_waitcnt lgkmcnt(0)
	v_mfma_f32_32x32x16_bf16 v[0:15], v[184:187], v[188:191], v[0:15]
	s_waitcnt vmcnt(16)
	ds_write_b128 v224, v[96:99] offset:16384
	ds_write_b128 v224, v[100:103] offset:24576
	ds_write_b128 v225, v[104:107] offset:17408
	ds_write_b128 v225, v[108:111] offset:25600
	ds_write_b128 v226, v[112:115] offset:18432
	ds_write_b128 v226, v[116:119] offset:26624
	ds_write_b128 v227, v[120:123] offset:19456
	ds_write_b128 v227, v[124:127] offset:27648
	ds_write_b128 v224, v[128:131] offset:20480
	ds_write_b128 v224, v[132:135] offset:28672
	ds_write_b128 v225, v[136:139] offset:21504
	ds_write_b128 v225, v[140:143] offset:29696
	ds_write_b128 v226, v[144:147] offset:22528
	ds_write_b128 v226, v[148:151] offset:30720
	ds_write_b128 v227, v[152:155] offset:23552
	ds_write_b128 v227, v[156:159] offset:31744
	s_waitcnt lgkmcnt(0)
	global_load_dwordx4 v[96:99], v[192:193], off offset:1792
	global_load_dwordx4 v[100:103], v[208:209], off offset:1792
	global_load_dwordx4 v[104:107], v[194:195], off offset:1792
	global_load_dwordx4 v[108:111], v[210:211], off offset:1792
	global_load_dwordx4 v[112:115], v[196:197], off offset:1792
	global_load_dwordx4 v[116:119], v[212:213], off offset:1792
	global_load_dwordx4 v[120:123], v[198:199], off offset:1792
	global_load_dwordx4 v[124:127], v[214:215], off offset:1792
	global_load_dwordx4 v[128:131], v[200:201], off offset:1792
	global_load_dwordx4 v[132:135], v[216:217], off offset:1792
	global_load_dwordx4 v[136:139], v[202:203], off offset:1792
	global_load_dwordx4 v[140:143], v[218:219], off offset:1792
	global_load_dwordx4 v[144:147], v[204:205], off offset:1792
	global_load_dwordx4 v[148:151], v[220:221], off offset:1792
	global_load_dwordx4 v[152:155], v[206:207], off offset:1792
	global_load_dwordx4 v[156:159], v[222:223], off offset:1792
	ds_read_b128 v[160:163], v228 offset:16384
	ds_read_b128 v[164:167], v228 offset:24576
	ds_read_b128 v[168:171], v229 offset:16384
	ds_read_b128 v[172:175], v229 offset:24576
	ds_read_b128 v[176:179], v230 offset:16384
	ds_read_b128 v[180:183], v230 offset:24576
	ds_read_b128 v[184:187], v231 offset:16384
	ds_read_b128 v[188:191], v231 offset:24576
	s_waitcnt lgkmcnt(6)
	v_mfma_f32_32x32x16_bf16 v[0:15], v[160:163], v[164:167], v[0:15]
	s_waitcnt lgkmcnt(4)
	v_mfma_f32_32x32x16_bf16 v[0:15], v[168:171], v[172:175], v[0:15]
	s_waitcnt lgkmcnt(2)
	v_mfma_f32_32x32x16_bf16 v[0:15], v[176:179], v[180:183], v[0:15]
	s_waitcnt lgkmcnt(0)
	v_mfma_f32_32x32x16_bf16 v[0:15], v[184:187], v[188:191], v[0:15]
	ds_read_b128 v[160:163], v232 offset:16384
	ds_read_b128 v[164:167], v232 offset:24576
	ds_read_b128 v[168:171], v233 offset:16384
	ds_read_b128 v[172:175], v233 offset:24576
	ds_read_b128 v[176:179], v234 offset:16384
	ds_read_b128 v[180:183], v234 offset:24576
	ds_read_b128 v[184:187], v235 offset:16384
	ds_read_b128 v[188:191], v235 offset:24576
	s_waitcnt lgkmcnt(6)
	v_mfma_f32_32x32x16_bf16 v[0:15], v[160:163], v[164:167], v[0:15]
	s_waitcnt lgkmcnt(4)
	v_mfma_f32_32x32x16_bf16 v[0:15], v[168:171], v[172:175], v[0:15]
	s_waitcnt lgkmcnt(2)
	v_mfma_f32_32x32x16_bf16 v[0:15], v[176:179], v[180:183], v[0:15]
	s_waitcnt lgkmcnt(0)
	v_mfma_f32_32x32x16_bf16 v[0:15], v[184:187], v[188:191], v[0:15]
	s_waitcnt vmcnt(16)
	ds_write_b128 v224, v[32:35] offset:0
	ds_write_b128 v224, v[36:39] offset:8192
	ds_write_b128 v225, v[40:43] offset:1024
	ds_write_b128 v225, v[44:47] offset:9216
	ds_write_b128 v226, v[48:51] offset:2048
	ds_write_b128 v226, v[52:55] offset:10240
	ds_write_b128 v227, v[56:59] offset:3072
	ds_write_b128 v227, v[60:63] offset:11264
	ds_write_b128 v224, v[64:67] offset:4096
	ds_write_b128 v224, v[68:71] offset:12288
	ds_write_b128 v225, v[72:75] offset:5120
	ds_write_b128 v225, v[76:79] offset:13312
	ds_write_b128 v226, v[80:83] offset:6144
	ds_write_b128 v226, v[84:87] offset:14336
	ds_write_b128 v227, v[88:91] offset:7168
	ds_write_b128 v227, v[92:95] offset:15360
	s_waitcnt lgkmcnt(0)
	ds_read_b128 v[160:163], v228 offset:0
	ds_read_b128 v[164:167], v228 offset:8192
	ds_read_b128 v[168:171], v229 offset:0
	ds_read_b128 v[172:175], v229 offset:8192
	ds_read_b128 v[176:179], v230 offset:0
	ds_read_b128 v[180:183], v230 offset:8192
	ds_read_b128 v[184:187], v231 offset:0
	ds_read_b128 v[188:191], v231 offset:8192
	s_waitcnt lgkmcnt(6)
	v_mfma_f32_32x32x16_bf16 v[0:15], v[160:163], v[164:167], v[0:15]
	s_waitcnt lgkmcnt(4)
	v_mfma_f32_32x32x16_bf16 v[0:15], v[168:171], v[172:175], v[0:15]
	s_waitcnt lgkmcnt(2)
	v_mfma_f32_32x32x16_bf16 v[0:15], v[176:179], v[180:183], v[0:15]
	s_waitcnt lgkmcnt(0)
	v_mfma_f32_32x32x16_bf16 v[0:15], v[184:187], v[188:191], v[0:15]
	ds_read_b128 v[160:163], v232 offset:0
	ds_read_b128 v[164:167], v232 offset:8192
	ds_read_b128 v[168:171], v233 offset:0
	ds_read_b128 v[172:175], v233 offset:8192
	ds_read_b128 v[176:179], v234 offset:0
	ds_read_b128 v[180:183], v234 offset:8192
	ds_read_b128 v[184:187], v235 offset:0
	ds_read_b128 v[188:191], v235 offset:8192
	s_waitcnt lgkmcnt(6)
	v_mfma_f32_32x32x16_bf16 v[0:15], v[160:163], v[164:167], v[0:15]
	s_waitcnt lgkmcnt(4)
	v_mfma_f32_32x32x16_bf16 v[0:15], v[168:171], v[172:175], v[0:15]
	s_waitcnt lgkmcnt(2)
	v_mfma_f32_32x32x16_bf16 v[0:15], v[176:179], v[180:183], v[0:15]
	s_waitcnt lgkmcnt(0)
	v_mfma_f32_32x32x16_bf16 v[0:15], v[184:187], v[188:191], v[0:15]
	s_waitcnt vmcnt(0)
	ds_write_b128 v224, v[96:99] offset:16384
	ds_write_b128 v224, v[100:103] offset:24576
	ds_write_b128 v225, v[104:107] offset:17408
	ds_write_b128 v225, v[108:111] offset:25600
	ds_write_b128 v226, v[112:115] offset:18432
	ds_write_b128 v226, v[116:119] offset:26624
	ds_write_b128 v227, v[120:123] offset:19456
	ds_write_b128 v227, v[124:127] offset:27648
	ds_write_b128 v224, v[128:131] offset:20480
	ds_write_b128 v224, v[132:135] offset:28672
	ds_write_b128 v225, v[136:139] offset:21504
	ds_write_b128 v225, v[140:143] offset:29696
	ds_write_b128 v226, v[144:147] offset:22528
	ds_write_b128 v226, v[148:151] offset:30720
	ds_write_b128 v227, v[152:155] offset:23552
	ds_write_b128 v227, v[156:159] offset:31744
	s_waitcnt lgkmcnt(0)
	ds_read_b128 v[160:163], v228 offset:16384
	ds_read_b128 v[164:167], v228 offset:24576
	ds_read_b128 v[168:171], v229 offset:16384
	ds_read_b128 v[172:175], v229 offset:24576
	ds_read_b128 v[176:179], v230 offset:16384
	ds_read_b128 v[180:183], v230 offset:24576
	ds_read_b128 v[184:187], v231 offset:16384
	ds_read_b128 v[188:191], v231 offset:24576
	s_waitcnt lgkmcnt(6)
	v_mfma_f32_32x32x16_bf16 v[0:15], v[160:163], v[164:167], v[0:15]
	s_waitcnt lgkmcnt(4)
	v_mfma_f32_32x32x16_bf16 v[0:15], v[168:171], v[172:175], v[0:15]
	s_waitcnt lgkmcnt(2)
	v_mfma_f32_32x32x16_bf16 v[0:15], v[176:179], v[180:183], v[0:15]
	s_waitcnt lgkmcnt(0)
	v_mfma_f32_32x32x16_bf16 v[0:15], v[184:187], v[188:191], v[0:15]
	ds_read_b128 v[160:163], v232 offset:16384
	ds_read_b128 v[164:167], v232 offset:24576
	ds_read_b128 v[168:171], v233 offset:16384
	ds_read_b128 v[172:175], v233 offset:24576
	ds_read_b128 v[176:179], v234 offset:16384
	ds_read_b128 v[180:183], v234 offset:24576
	ds_read_b128 v[184:187], v235 offset:16384
	ds_read_b128 v[188:191], v235 offset:24576
	s_waitcnt lgkmcnt(6)
	v_mfma_f32_32x32x16_bf16 v[0:15], v[160:163], v[164:167], v[0:15]
	s_waitcnt lgkmcnt(4)
	v_mfma_f32_32x32x16_bf16 v[0:15], v[168:171], v[172:175], v[0:15]
	s_waitcnt lgkmcnt(2)
	v_mfma_f32_32x32x16_bf16 v[0:15], v[176:179], v[180:183], v[0:15]
	s_waitcnt lgkmcnt(0)
	v_mfma_f32_32x32x16_bf16 v[0:15], v[184:187], v[188:191], v[0:15]
	s_andn2_b64 vcc, exec, s[6:7]
	s_mov_b64 s[6:7], -1
	s_cbranch_vccnz .LBB0_536
	v_lshl_add_u32 v44, s24, 5, v29
	v_ashrrev_i32_e32 v45, 31, v44
	v_lshl_add_u64 v[40:41], v[44:45], 2, s[12:13]
	global_load_dwordx4 v[24:27], v[40:41], off
	global_load_dwordx4 v[32:35], v[40:41], off offset:32
	global_load_dwordx4 v[36:39], v[40:41], off offset:64
	s_nop 0
	global_load_dwordx4 v[40:43], v[40:41], off offset:96
	s_lshl_b32 s16, s25, 6
	v_or_b32_e32 v48, 1, v44
	v_or_b32_e32 v50, 2, v44
	v_or_b32_e32 v52, 3, v44
	v_lshl_add_u64 v[46:47], v[18:19], 0, s[16:17]
	v_lshlrev_b64 v[44:45], 11, v[44:45]
	v_ashrrev_i32_e32 v49, 31, v48
	v_ashrrev_i32_e32 v51, 31, v50
	v_ashrrev_i32_e32 v53, 31, v52
	v_lshl_add_u64 v[44:45], v[46:47], 0, v[44:45]
	v_lshlrev_b64 v[48:49], 11, v[48:49]
	v_lshlrev_b64 v[50:51], 11, v[50:51]
	v_lshlrev_b64 v[52:53], 11, v[52:53]
	v_lshl_add_u64 v[48:49], v[46:47], 0, v[48:49]
	v_lshl_add_u64 v[50:51], v[46:47], 0, v[50:51]
	v_lshl_add_u64 v[46:47], v[46:47], 0, v[52:53]
	v_add_co_u32_e32 v52, vcc, s18, v44
	s_nop 1
	v_addc_co_u32_e32 v53, vcc, 0, v45, vcc
	v_add_co_u32_e32 v54, vcc, s19, v44
	s_waitcnt vmcnt(3)
	v_mul_f32_e32 v16, v0, v24
	v_addc_co_u32_e32 v55, vcc, 0, v45, vcc
	v_add_co_u32_e32 v56, vcc, s20, v44
	v_mul_f32_e32 v24, v1, v25
	s_nop 0
	v_addc_co_u32_e32 v57, vcc, 0, v45, vcc
	v_add_co_u32_e32 v58, vcc, s21, v44
	v_mul_f32_e32 v25, v2, v26
	s_nop 0
	v_addc_co_u32_e32 v59, vcc, 0, v45, vcc
	v_add_co_u32_e32 v60, vcc, s22, v44
	v_mul_f32_e32 v26, v3, v27
	s_nop 0
	v_addc_co_u32_e32 v61, vcc, 0, v45, vcc
	s_waitcnt vmcnt(2)
	v_mul_f32_e32 v27, v4, v32
	v_mul_f32_e32 v31, v5, v33
	v_mul_f32_e32 v32, v6, v34
	v_mul_f32_e32 v33, v7, v35
	s_waitcnt vmcnt(1)
	v_mul_f32_e32 v34, v8, v36
	v_mul_f32_e32 v35, v9, v37
	v_mul_f32_e32 v36, v10, v38
	v_mul_f32_e32 v37, v11, v39
	s_waitcnt vmcnt(0)
	v_mul_f32_e32 v38, v12, v40
	v_mul_f32_e32 v39, v13, v41
	v_cvt_pk_bf16_f32 v16, v16, s0
	v_cvt_pk_bf16_f32 v24, v24, s0
	v_cvt_pk_bf16_f32 v25, v25, s0
	v_cvt_pk_bf16_f32 v26, v26, s0
	v_cvt_pk_bf16_f32 v27, v27, s0
	v_cvt_pk_bf16_f32 v31, v31, s0
	v_cvt_pk_bf16_f32 v32, v32, s0
	v_cvt_pk_bf16_f32 v33, v33, s0
	v_cvt_pk_bf16_f32 v34, v34, s0
	v_cvt_pk_bf16_f32 v35, v35, s0
	v_cvt_pk_bf16_f32 v36, v36, s0
	v_cvt_pk_bf16_f32 v37, v37, s0
	v_cvt_pk_bf16_f32 v38, v38, s0
	v_cvt_pk_bf16_f32 v39, v39, s0
	global_store_short v[44:45], v16, off
	global_store_short v[48:49], v24, off
	global_store_short v[50:51], v25, off
	global_store_short v[46:47], v26, off
	global_store_short v[54:55], v27, off offset:-4096
	global_store_short v[52:53], v31, off offset:2048
	global_store_short v[54:55], v32, off
	global_store_short v[54:55], v33, off offset:2048
	global_store_short v[58:59], v34, off offset:-4096
	global_store_short v[56:57], v35, off offset:2048
	global_store_short v[58:59], v36, off
	global_store_short v[58:59], v37, off offset:2048
	global_store_short v[60:61], v38, off
	global_store_short v[60:61], v39, off offset:2048
	v_mul_f32_e32 v16, v14, v42
	v_add_co_u32_e32 v24, vcc, 0xd000, v44
	v_cvt_pk_bf16_f32 v16, v16, s0
	s_nop 0
	v_addc_co_u32_e32 v25, vcc, 0, v45, vcc
	global_store_short v[24:25], v16, off
	v_mul_f32_e32 v16, v15, v43
	v_cvt_pk_bf16_f32 v16, v16, s0
	global_store_short v[24:25], v16, off offset:2048
	s_cbranch_execnz .LBB0_531
	s_branch .LBB0_537
